# consumer waves s_setprio 3 during the recurrence
# speedup vs baseline: 1.0055x; 1.0009x over previous
.LBB0_679:
	s_lshl_b32 s6, s25, 2
	s_and_b32 s6, s6, 28
	s_ashr_i32 s7, s25, 6
	v_readlane_b32 s8, v253, 44
	s_add_i32 s6, s6, s7
	v_readlane_b32 s9, v253, 45
	s_ashr_i32 s26, s6, 3
	s_and_b32 s27, s6, 7
	s_mov_b64 s[6:7], -1
	s_and_b64 vcc, exec, s[8:9]
	s_cbranch_vccz .LBB0_694
	s_and_b32 s6, s25, 56
	v_add_u32_e32 v46, s6, v57
	s_lshr_b32 s6, s25, 6
	s_and_b32 s7, s24, 4
	s_add_i32 s7, s7, s6
	s_and_b32 s6, s7, 7
	s_mul_i32 s29, s26, 0x808000
	s_lshl_b32 s6, s6, 8
	s_mul_hi_i32 s28, s26, 0x808000
	s_or_b32 s6, s29, s6
	v_ashrrev_i32_e32 v47, 31, v46
	s_waitcnt lgkmcnt(0)
	s_barrier
	v_mov_b32_e32 v0, s6
	v_mov_b32_e32 v1, s28
	v_lshl_add_u64 v[0:1], v[46:47], 2, v[0:1]
	v_mov_b32_e32 v162, v163
	v_lshlrev_b32_e32 v86, 2, v46
	v_lshl_add_u64 v[48:49], v[44:45], 0, v[0:1]
	v_lshl_add_u64 v[50:51], s[90:91], 0, v[0:1]
	s_mov_b32 s30, 0
	s_mov_b64 s[88:89], 0
	s_movk_i32 s31, 0x1010
	v_mov_b64_e32 v[52:53], v[162:163]
	v_lshrrev_b32_e32 v2, 1, v57
	v_and_b32_e32 v3, 1, v57
	v_mul_u32_u24_e32 v2, 0x1200, v2
	v_lshl_add_u32 v2, v3, 6, v2
	v_add_u32_e32 v2, 0x1c000, v2
	v_mbcnt_lo_u32_b32 v3, -1, 0
	v_mbcnt_hi_u32_b32 v3, -1, v3
	v_and_b32_e32 v87, 31, v3
	v_lshrrev_b32_e32 v3, 1, v87
	v_lshl_add_u32 v91, v3, 2, v2
	v_mul_u32_u24_e32 v3, 0x90, v87
	v_add_u32_e32 v92, v3, v2
	v_lshlrev_b32_e32 v94, 11, v87
	v_mov_b32_e32 v95, 0
	s_setprio 3
	s_branch .LBB0_682

.LBB0_691:
	s_setprio 0
	v_add_u32_e32 v0, 0x6000, v60
	ds_read2_b32 v[0:1], v0 offset0:1 offset1:3
	s_waitcnt lgkmcnt(0)
	v_mul_f32_e32 v1, v53, v1
	v_fmac_f32_e32 v1, v52, v0
	s_nop 1
	v_add_f32_dpp v0, v1, v1 quad_perm:[1,0,3,2] row_mask:0xf bank_mask:0xf bound_ctrl:1
	v_mov_b32_e32 v1, v163
	s_nop 0
	v_add_f32_dpp v0, v0, v0 quad_perm:[2,3,0,1] row_mask:0xf bank_mask:0xf bound_ctrl:1
	v_mov_b32_dpp v1, v1 quad_perm:[1,0,3,2] row_mask:0xf bank_mask:0xf
	v_add_f32_e32 v1, 0, v1
	v_add_f32_dpp v0, v0, v0 row_half_mirror row_mask:0xf bank_mask:0xf bound_ctrl:1
	s_nop 0
	v_add_f32_dpp v1, v1, v1 quad_perm:[2,3,0,1] row_mask:0xf bank_mask:0xf bound_ctrl:1
	v_add_f32_dpp v0, v0, v0 row_mirror row_mask:0xf bank_mask:0xf bound_ctrl:1
	s_nop 0
	v_add_f32_dpp v1, v1, v1 row_half_mirror row_mask:0xf bank_mask:0xf bound_ctrl:1
	s_nop 1
	v_add_f32_dpp v1, v1, v1 row_mirror row_mask:0xf bank_mask:0xf bound_ctrl:1
	s_nop 1
	v_permlane16_swap_b32_e32 v0, v1
	v_add_f32_e32 v0, v0, v1
	s_nop 1
	v_mov_b32_dpp v0, v0 row_bcast:15 row_mask:0xa bank_mask:0xf
	s_and_saveexec_b64 s[6:7], s[76:77]
	s_cbranch_execz .LBB0_693
	s_add_u32 s8, s22, s29
	s_addc_u32 s9, s23, s28
	s_lshl_b32 s28, s27, 8
	s_add_u32 s8, s8, s28
	s_addc_u32 s9, s9, 0
	v_lshl_add_u64 v[2:3], v[46:47], 2, s[8:9]
	v_add_co_u32_e32 v2, vcc, 0x807000, v2
	s_nop 1
	v_addc_co_u32_e32 v3, vcc, 0, v3, vcc
	global_store_dword v[2:3], v0, off offset:2048
